# POST transpose store sections: the four LDS reads issued together with counted lgkmcnt waits instead of read-wait-store four times
# speedup vs baseline: 1.0088x; 1.0088x over previous
; #define LAS __attribute__((address_space(3)))
; __device__ __forceinline__ int perm16(int row) { const int q = (row >> 2) & 3; const int q2 = (q == 1) ? 2 : (q == 2 ? 1 : q); return (row & ~15) | (q2 << 2) | (row & 3); }
; template <bool PERMK, class F> __device__ __forceinline__ void post_transpose(const bf16_t* px, int c0, LAS unsigned short* Lt, int tid, F&& destrow) {
;     u32x4 v[4];
; #pragma unroll
;     for (int j = 0; j < 4; ++j) { const int c = tid + j * NTHREADS; v[j] = *(const u32x4*)(px + (size_t)(c >> 4) * NIN + c0 + (c & 15) * 8); }
; #pragma unroll
;     for (int j = 0; j < 4; ++j) {
;         const int c = tid + j * NTHREADS, row = c >> 4, ch = c & 15;
;         const int pr = (PERMK ? perm16(row) : row) ^ (ch << 3);
;         LAS unsigned short* d = Lt + (ch * 8) * 136 + pr;
;         d[0] = (unsigned short)(v[j].x & 0xffff); d[136] = (unsigned short)(v[j].x >> 16); d[2 * 136] = (unsigned short)(v[j].y & 0xffff); d[3 * 136] = (unsigned short)(v[j].y >> 16);
;         d[4 * 136] = (unsigned short)(v[j].z & 0xffff); d[5 * 136] = (unsigned short)(v[j].z >> 16); d[6 * 136] = (unsigned short)(v[j].w & 0xffff); d[7 * 136] = (unsigned short)(v[j].w >> 16);
;     }
;     __syncthreads();
; #pragma unroll
;     for (int j = 0; j < 4; ++j) {
;         const int c = tid + j * NTHREADS, col = c >> 4, ch = c & 15;
;         const u32x4 w = *(const LAS u32x4*)(Lt + col * 136 + ((ch * 8) ^ (((col >> 3) & 15) << 3)));
;         *(u32x4*)(destrow(col) + ch * 8) = w;
;     }
;     __syncthreads();
; __device__ __forceinline__ void post_phase(const Params& p, int l, LAS unsigned char* lds, int tid) {
;     ...
;                 if (isx) post_transpose<false>(px, 768 + g * 128, Lt, tid, [&](int col) { return ZT + ((size_t)((col >> 6) * 2048 + b * 256 + g * 64 + (col & 63))) * 4096 + n0; });
;                 else     post_transpose<false>(px, 768 + g * 128, Lt, tid, [&](int col) { return ZTC + ((size_t)(b * 256 + g * 64 + (col & 63))) * 512 + (col >> 6) * 256 + n0; });
.LBB0_360:
	s_and_b64 vcc, exec, s[0:1]
	s_cbranch_vccz .LBB0_377
	v_lshlrev_b32_e32 v186, 1, v48
	v_lshl_add_u64 v[8:9], s[46:47], 0, v[186:187]
	v_lshl_add_u64 v[14:15], v[8:9], 0, v[50:51]
	global_load_dwordx4 v[16:19], v[14:15], off offset:1536
	v_lshl_add_u64 v[12:13], v[8:9], 0, v[52:53]
	v_lshl_add_u64 v[10:11], v[8:9], 0, v[54:55]
	v_lshl_add_u64 v[8:9], v[8:9], 0, v[56:57]
	global_load_dwordx4 v[160:163], v[12:13], off offset:1536
	global_load_dwordx4 v[164:167], v[10:11], off offset:1536
	global_load_dwordx4 v[168:171], v[8:9], off offset:1536
	s_lshl_b32 s76, s9, 1
	s_lshl_b32 s10, s8, 8
	v_lshl_add_u64 v[6:7], v[60:61], 0, s[76:77]
	v_lshl_add_u64 v[4:5], v[64:65], 0, s[76:77]
	v_lshl_add_u64 v[2:3], v[68:69], 0, s[76:77]
	v_lshl_add_u64 v[0:1], v[72:73], 0, s[76:77]
	s_mov_b64 s[0:1], -1
	s_and_b64 vcc, exec, s[94:95]
	s_waitcnt vmcnt(3)
	ds_write_b16 v67, v16
	ds_write_b16_d16_hi v67, v16 offset:272
	ds_write_b16 v67, v17 offset:544
	ds_write_b16_d16_hi v67, v17 offset:816
	ds_write_b16 v67, v18 offset:1088
	ds_write_b16_d16_hi v67, v18 offset:1360
	ds_write_b16 v67, v19 offset:1632
	ds_write_b16_d16_hi v67, v19 offset:1904
	s_waitcnt vmcnt(2)
	ds_write_b16 v71, v160
	ds_write_b16_d16_hi v71, v160 offset:272
	ds_write_b16 v71, v161 offset:544
	ds_write_b16_d16_hi v71, v161 offset:816
	ds_write_b16 v71, v162 offset:1088
	ds_write_b16_d16_hi v71, v162 offset:1360
	ds_write_b16 v71, v163 offset:1632
	ds_write_b16_d16_hi v71, v163 offset:1904
	s_waitcnt vmcnt(1)
	ds_write_b16 v77, v164
	ds_write_b16_d16_hi v77, v164 offset:272
	ds_write_b16 v77, v165 offset:544
	ds_write_b16_d16_hi v77, v165 offset:816
	ds_write_b16 v77, v166 offset:1088
	ds_write_b16_d16_hi v77, v166 offset:1360
	ds_write_b16 v77, v167 offset:1632
	ds_write_b16_d16_hi v77, v167 offset:1904
	s_waitcnt vmcnt(0)
	ds_write_b16 v106, v168
	ds_write_b16_d16_hi v106, v168 offset:272
	ds_write_b16 v106, v169 offset:544
	ds_write_b16_d16_hi v106, v169 offset:816
	ds_write_b16 v106, v170 offset:1088
	ds_write_b16_d16_hi v106, v170 offset:1360
	ds_write_b16 v106, v171 offset:1632
	ds_write_b16_d16_hi v106, v171 offset:1904
	s_waitcnt lgkmcnt(0)
	s_cbranch_vccz .LBB0_363
	s_barrier
	ds_read_b128 v[172:175], v107
	ds_read_b128 v[176:179], v108
	ds_read_b128 v[180:183], v109
	ds_read_b128 v[212:215], v110
	v_or_b32_e32 v186, s10, v58
	v_lshlrev_b64 v[20:21], 10, v[186:187]
	v_lshl_add_u64 v[20:21], v[6:7], 0, v[20:21]
	v_or_b32_e32 v186, s10, v62
	s_waitcnt lgkmcnt(3)
	global_store_dwordx4 v[20:21], v[172:175], off
	v_lshlrev_b64 v[20:21], 10, v[186:187]
	v_lshl_add_u64 v[20:21], v[4:5], 0, v[20:21]
	v_or_b32_e32 v186, s10, v66
	s_mov_b64 s[0:1], 0
	s_waitcnt lgkmcnt(2)
	global_store_dwordx4 v[20:21], v[176:179], off
	v_lshlrev_b64 v[20:21], 10, v[186:187]
	v_lshl_add_u64 v[20:21], v[2:3], 0, v[20:21]
	v_or_b32_e32 v186, s10, v70
	s_waitcnt lgkmcnt(1)
	global_store_dwordx4 v[20:21], v[180:183], off
	v_lshlrev_b64 v[20:21], 10, v[186:187]
	v_lshl_add_u64 v[20:21], v[0:1], 0, v[20:21]
	s_waitcnt lgkmcnt(0)
	global_store_dwordx4 v[20:21], v[212:215], off
	s_barrier
.LBB0_363:
	s_lshl_b32 s4, s7, 8
	s_lshl_b32 s76, s6, 1
	v_add_u32_e32 v24, s4, v111
	v_lshl_add_u64 v[16:17], v[74:75], 0, s[76:77]
	v_add_u32_e32 v22, s4, v112
	v_add_u32_e32 v20, s4, v113
	s_andn2_b64 vcc, exec, s[0:1]
	v_add_u32_e32 v18, s4, v114
	s_cbranch_vccnz .LBB0_365
	s_barrier
	ds_read_b128 v[172:175], v107
	ds_read_b128 v[176:179], v108
	ds_read_b128 v[180:183], v109
	ds_read_b128 v[212:215], v110
	v_ashrrev_i32_e32 v25, 31, v24
	v_lshlrev_b64 v[30:31], 13, v[24:25]
	v_lshl_add_u64 v[30:31], v[16:17], 0, v[30:31]
	v_ashrrev_i32_e32 v23, 31, v22
	s_waitcnt lgkmcnt(3)
	global_store_dwordx4 v[30:31], v[172:175], off
	v_lshlrev_b64 v[30:31], 13, v[22:23]
	v_lshl_add_u64 v[30:31], v[16:17], 0, v[30:31]
	v_ashrrev_i32_e32 v21, 31, v20
	v_ashrrev_i32_e32 v19, 31, v18
	s_waitcnt lgkmcnt(2)
	global_store_dwordx4 v[30:31], v[176:179], off
	v_lshlrev_b64 v[30:31], 13, v[20:21]
	v_lshl_add_u64 v[30:31], v[16:17], 0, v[30:31]
	s_waitcnt lgkmcnt(1)
	global_store_dwordx4 v[30:31], v[180:183], off
	v_lshlrev_b64 v[30:31], 13, v[18:19]
	v_lshl_add_u64 v[30:31], v[16:17], 0, v[30:31]
	s_waitcnt lgkmcnt(0)
	global_store_dwordx4 v[30:31], v[212:215], off
	s_barrier
.LBB0_365:
	global_load_dwordx4 v[26:29], v[14:15], off offset:1792
	global_load_dwordx4 v[160:163], v[12:13], off offset:1792
	global_load_dwordx4 v[164:167], v[10:11], off offset:1792
	global_load_dwordx4 v[168:171], v[8:9], off offset:1792
	v_cndmask_b32_e64 v19, 0, 1, s[94:95]
	s_mov_b64 s[4:5], -1
	v_cmp_ne_u32_e64 s[0:1], 1, v19
	s_andn2_b64 vcc, exec, s[94:95]
	s_waitcnt vmcnt(3)
	ds_write_b16 v67, v26
	ds_write_b16_d16_hi v67, v26 offset:272
	ds_write_b16 v67, v27 offset:544
	ds_write_b16_d16_hi v67, v27 offset:816
	ds_write_b16 v67, v28 offset:1088
	ds_write_b16_d16_hi v67, v28 offset:1360
	ds_write_b16 v67, v29 offset:1632
	ds_write_b16_d16_hi v67, v29 offset:1904
	s_waitcnt vmcnt(2)
	ds_write_b16 v71, v160
	ds_write_b16_d16_hi v71, v160 offset:272
	ds_write_b16 v71, v161 offset:544
	ds_write_b16_d16_hi v71, v161 offset:816
	ds_write_b16 v71, v162 offset:1088
	ds_write_b16_d16_hi v71, v162 offset:1360
	ds_write_b16 v71, v163 offset:1632
	ds_write_b16_d16_hi v71, v163 offset:1904
	s_waitcnt vmcnt(1)
	ds_write_b16 v77, v164
	ds_write_b16_d16_hi v77, v164 offset:272
	ds_write_b16 v77, v165 offset:544
	ds_write_b16_d16_hi v77, v165 offset:816
	ds_write_b16 v77, v166 offset:1088
	ds_write_b16_d16_hi v77, v166 offset:1360
	ds_write_b16 v77, v167 offset:1632
	ds_write_b16_d16_hi v77, v167 offset:1904
	s_waitcnt vmcnt(0)
	ds_write_b16 v106, v168
	ds_write_b16_d16_hi v106, v168 offset:272
	ds_write_b16 v106, v169 offset:544
	ds_write_b16_d16_hi v106, v169 offset:816
	ds_write_b16 v106, v170 offset:1088
	ds_write_b16_d16_hi v106, v170 offset:1360
	ds_write_b16 v106, v171 offset:1632
	ds_write_b16_d16_hi v106, v171 offset:1904
	s_waitcnt lgkmcnt(0)
	s_cbranch_vccnz .LBB0_367
	s_barrier
	ds_read_b128 v[172:175], v107
	ds_read_b128 v[176:179], v108
	ds_read_b128 v[180:183], v109
	ds_read_b128 v[212:215], v110
	s_or_b32 s4, s10, 64
	v_or_b32_e32 v186, s4, v58
	v_lshlrev_b64 v[30:31], 10, v[186:187]
	v_lshl_add_u64 v[30:31], v[6:7], 0, v[30:31]
	s_waitcnt lgkmcnt(3)
	global_store_dwordx4 v[30:31], v[172:175], off
	v_or_b32_e32 v186, s4, v62
	v_lshlrev_b64 v[30:31], 10, v[186:187]
	v_lshl_add_u64 v[30:31], v[4:5], 0, v[30:31]
	v_or_b32_e32 v186, s4, v66
	s_waitcnt lgkmcnt(2)
	global_store_dwordx4 v[30:31], v[176:179], off
	v_lshlrev_b64 v[30:31], 10, v[186:187]
	v_lshl_add_u64 v[30:31], v[2:3], 0, v[30:31]
	v_or_b32_e32 v186, s4, v70
	s_mov_b64 s[4:5], 0
	s_waitcnt lgkmcnt(1)
	global_store_dwordx4 v[30:31], v[180:183], off
	v_lshlrev_b64 v[30:31], 10, v[186:187]
	v_lshl_add_u64 v[30:31], v[0:1], 0, v[30:31]
	s_waitcnt lgkmcnt(0)
	global_store_dwordx4 v[30:31], v[212:215], off
	s_barrier
; #define LAS __attribute__((address_space(3)))
; __device__ __forceinline__ int perm16(int row) { const int q = (row >> 2) & 3; const int q2 = (q == 1) ? 2 : (q == 2 ? 1 : q); return (row & ~15) | (q2 << 2) | (row & 3); }
; template <bool PERMK, class F> __device__ __forceinline__ void post_transpose(const bf16_t* px, int c0, LAS unsigned short* Lt, int tid, F&& destrow) {
;     u32x4 v[4];
; #pragma unroll
;     for (int j = 0; j < 4; ++j) { const int c = tid + j * NTHREADS; v[j] = *(const u32x4*)(px + (size_t)(c >> 4) * NIN + c0 + (c & 15) * 8); }
; #pragma unroll
;     for (int j = 0; j < 4; ++j) {
;         const int c = tid + j * NTHREADS, row = c >> 4, ch = c & 15;
;         const int pr = (PERMK ? perm16(row) : row) ^ (ch << 3);
;         LAS unsigned short* d = Lt + (ch * 8) * 136 + pr;
;         d[0] = (unsigned short)(v[j].x & 0xffff); d[136] = (unsigned short)(v[j].x >> 16); d[2 * 136] = (unsigned short)(v[j].y & 0xffff); d[3 * 136] = (unsigned short)(v[j].y >> 16);
;         d[4 * 136] = (unsigned short)(v[j].z & 0xffff); d[5 * 136] = (unsigned short)(v[j].z >> 16); d[6 * 136] = (unsigned short)(v[j].w & 0xffff); d[7 * 136] = (unsigned short)(v[j].w >> 16);
;     }
;     __syncthreads();
; #pragma unroll
;     for (int j = 0; j < 4; ++j) {
;         const int c = tid + j * NTHREADS, col = c >> 4, ch = c & 15;
;         const u32x4 w = *(const LAS u32x4*)(Lt + col * 136 + ((ch * 8) ^ (((col >> 3) & 15) << 3)));
;         *(u32x4*)(destrow(col) + ch * 8) = w;
;     }
;     __syncthreads();
; }
; __device__ __forceinline__ void post_phase(const Params& p, int l, LAS unsigned char* lds, int tid) {
;     ...
;             for (int g = 0; g < 4; ++g) {
;                 if (isx) post_transpose<false>(px, 768 + g * 128, Lt, tid, [&](int col) { return ZT + ((size_t)((col >> 6) * 2048 + b * 256 + g * 64 + (col & 63))) * 4096 + n0; });
;                 else     post_transpose<false>(px, 768 + g * 128, Lt, tid, [&](int col) { return ZTC + ((size_t)(b * 256 + g * 64 + (col & 63))) * 512 + (col >> 6) * 256 + n0; });
;             }
.LBB0_367:
	s_andn2_b64 vcc, exec, s[4:5]
	s_cbranch_vccnz .LBB0_369
	s_barrier
	ds_read_b128 v[172:175], v107
	ds_read_b128 v[176:179], v108
	ds_read_b128 v[180:183], v109
	ds_read_b128 v[212:215], v110
	v_or_b32_e32 v30, 64, v24
	v_ashrrev_i32_e32 v31, 31, v30
	v_lshlrev_b64 v[30:31], 13, v[30:31]
	v_lshl_add_u64 v[30:31], v[16:17], 0, v[30:31]
	s_waitcnt lgkmcnt(3)
	global_store_dwordx4 v[30:31], v[172:175], off
	v_or_b32_e32 v30, 64, v22
	v_ashrrev_i32_e32 v31, 31, v30
	v_lshlrev_b64 v[30:31], 13, v[30:31]
	v_lshl_add_u64 v[30:31], v[16:17], 0, v[30:31]
	s_waitcnt lgkmcnt(2)
	global_store_dwordx4 v[30:31], v[176:179], off
	v_or_b32_e32 v30, 64, v20
	v_ashrrev_i32_e32 v31, 31, v30
	v_lshlrev_b64 v[30:31], 13, v[30:31]
	v_lshl_add_u64 v[30:31], v[16:17], 0, v[30:31]
	s_waitcnt lgkmcnt(1)
	global_store_dwordx4 v[30:31], v[180:183], off
	v_or_b32_e32 v30, 64, v18
	v_ashrrev_i32_e32 v31, 31, v30
	v_lshlrev_b64 v[30:31], 13, v[30:31]
	v_lshl_add_u64 v[30:31], v[16:17], 0, v[30:31]
	s_waitcnt lgkmcnt(0)
	global_store_dwordx4 v[30:31], v[212:215], off
	s_barrier
.LBB0_369:
	global_load_dwordx4 v[26:29], v[14:15], off offset:2048
	global_load_dwordx4 v[160:163], v[12:13], off offset:2048
	global_load_dwordx4 v[164:167], v[10:11], off offset:2048
	global_load_dwordx4 v[168:171], v[8:9], off offset:2048
	s_mov_b64 s[4:5], -1
	s_and_b64 vcc, exec, s[0:1]
	s_waitcnt vmcnt(3)
	ds_write_b16 v67, v26
	ds_write_b16_d16_hi v67, v26 offset:272
	ds_write_b16 v67, v27 offset:544
	ds_write_b16_d16_hi v67, v27 offset:816
	ds_write_b16 v67, v28 offset:1088
	ds_write_b16_d16_hi v67, v28 offset:1360
	ds_write_b16 v67, v29 offset:1632
	ds_write_b16_d16_hi v67, v29 offset:1904
	s_waitcnt vmcnt(2)
	ds_write_b16 v71, v160
	ds_write_b16_d16_hi v71, v160 offset:272
	ds_write_b16 v71, v161 offset:544
	ds_write_b16_d16_hi v71, v161 offset:816
	ds_write_b16 v71, v162 offset:1088
	ds_write_b16_d16_hi v71, v162 offset:1360
	ds_write_b16 v71, v163 offset:1632
	ds_write_b16_d16_hi v71, v163 offset:1904
	s_waitcnt vmcnt(1)
	ds_write_b16 v77, v164
	ds_write_b16_d16_hi v77, v164 offset:272
	ds_write_b16 v77, v165 offset:544
	ds_write_b16_d16_hi v77, v165 offset:816
	ds_write_b16 v77, v166 offset:1088
	ds_write_b16_d16_hi v77, v166 offset:1360
	ds_write_b16 v77, v167 offset:1632
	ds_write_b16_d16_hi v77, v167 offset:1904
	s_waitcnt vmcnt(0)
	ds_write_b16 v106, v168
	ds_write_b16_d16_hi v106, v168 offset:272
	ds_write_b16 v106, v169 offset:544
	ds_write_b16_d16_hi v106, v169 offset:816
	ds_write_b16 v106, v170 offset:1088
	ds_write_b16_d16_hi v106, v170 offset:1360
	ds_write_b16 v106, v171 offset:1632
	ds_write_b16_d16_hi v106, v171 offset:1904
	s_waitcnt lgkmcnt(0)
	s_cbranch_vccnz .LBB0_371
	s_barrier
	ds_read_b128 v[172:175], v107
	ds_read_b128 v[176:179], v108
	ds_read_b128 v[180:183], v109
	ds_read_b128 v[212:215], v110
	s_or_b32 s4, s10, 0x80
	v_or_b32_e32 v186, s4, v58
	v_lshlrev_b64 v[30:31], 10, v[186:187]
	v_lshl_add_u64 v[30:31], v[6:7], 0, v[30:31]
	s_waitcnt lgkmcnt(3)
	global_store_dwordx4 v[30:31], v[172:175], off
	v_or_b32_e32 v186, s4, v62
	v_lshlrev_b64 v[30:31], 10, v[186:187]
	v_lshl_add_u64 v[30:31], v[4:5], 0, v[30:31]
	v_or_b32_e32 v186, s4, v66
	s_waitcnt lgkmcnt(2)
	global_store_dwordx4 v[30:31], v[176:179], off
	v_lshlrev_b64 v[30:31], 10, v[186:187]
	v_lshl_add_u64 v[30:31], v[2:3], 0, v[30:31]
	v_or_b32_e32 v186, s4, v70
	s_mov_b64 s[4:5], 0
	s_waitcnt lgkmcnt(1)
	global_store_dwordx4 v[30:31], v[180:183], off
	v_lshlrev_b64 v[30:31], 10, v[186:187]
	v_lshl_add_u64 v[30:31], v[0:1], 0, v[30:31]
	s_waitcnt lgkmcnt(0)
	global_store_dwordx4 v[30:31], v[212:215], off
	s_barrier
.LBB0_371:
	s_andn2_b64 vcc, exec, s[4:5]
	s_cbranch_vccnz .LBB0_373
	s_barrier
	ds_read_b128 v[172:175], v107
	ds_read_b128 v[176:179], v108
	ds_read_b128 v[180:183], v109
	ds_read_b128 v[212:215], v110
	v_or_b32_e32 v30, 0x80, v24
	v_ashrrev_i32_e32 v31, 31, v30
	v_lshlrev_b64 v[30:31], 13, v[30:31]
	v_lshl_add_u64 v[30:31], v[16:17], 0, v[30:31]
	s_waitcnt lgkmcnt(3)
	global_store_dwordx4 v[30:31], v[172:175], off
	v_or_b32_e32 v30, 0x80, v22
	v_ashrrev_i32_e32 v31, 31, v30
	v_lshlrev_b64 v[30:31], 13, v[30:31]
	v_lshl_add_u64 v[30:31], v[16:17], 0, v[30:31]
	s_waitcnt lgkmcnt(2)
	global_store_dwordx4 v[30:31], v[176:179], off
	v_or_b32_e32 v30, 0x80, v20
	v_ashrrev_i32_e32 v31, 31, v30
	v_lshlrev_b64 v[30:31], 13, v[30:31]
	v_lshl_add_u64 v[30:31], v[16:17], 0, v[30:31]
	s_waitcnt lgkmcnt(1)
	global_store_dwordx4 v[30:31], v[180:183], off
	v_or_b32_e32 v30, 0x80, v18
	v_ashrrev_i32_e32 v31, 31, v30
	v_lshlrev_b64 v[30:31], 13, v[30:31]
	v_lshl_add_u64 v[30:31], v[16:17], 0, v[30:31]
	s_waitcnt lgkmcnt(0)
	global_store_dwordx4 v[30:31], v[212:215], off
	s_barrier

; #define LAS __attribute__((address_space(3)))
; __device__ __forceinline__ int perm16(int row) { const int q = (row >> 2) & 3; const int q2 = (q == 1) ? 2 : (q == 2 ? 1 : q); return (row & ~15) | (q2 << 2) | (row & 3); }
; template <bool PERMK, class F> __device__ __forceinline__ void post_transpose(const bf16_t* px, int c0, LAS unsigned short* Lt, int tid, F&& destrow) {
;     u32x4 v[4];
; #pragma unroll
;     for (int j = 0; j < 4; ++j) { const int c = tid + j * NTHREADS; v[j] = *(const u32x4*)(px + (size_t)(c >> 4) * NIN + c0 + (c & 15) * 8); }
; #pragma unroll
;     for (int j = 0; j < 4; ++j) {
;         const int c = tid + j * NTHREADS, row = c >> 4, ch = c & 15;
;         const int pr = (PERMK ? perm16(row) : row) ^ (ch << 3);
;         LAS unsigned short* d = Lt + (ch * 8) * 136 + pr;
;         d[0] = (unsigned short)(v[j].x & 0xffff); d[136] = (unsigned short)(v[j].x >> 16); d[2 * 136] = (unsigned short)(v[j].y & 0xffff); d[3 * 136] = (unsigned short)(v[j].y >> 16);
;         d[4 * 136] = (unsigned short)(v[j].z & 0xffff); d[5 * 136] = (unsigned short)(v[j].z >> 16); d[6 * 136] = (unsigned short)(v[j].w & 0xffff); d[7 * 136] = (unsigned short)(v[j].w >> 16);
;     }
;     __syncthreads();
; #pragma unroll
;     for (int j = 0; j < 4; ++j) {
;         const int c = tid + j * NTHREADS, col = c >> 4, ch = c & 15;
;         const u32x4 w = *(const LAS u32x4*)(Lt + col * 136 + ((ch * 8) ^ (((col >> 3) & 15) << 3)));
;         *(u32x4*)(destrow(col) + ch * 8) = w;
;     }
;     __syncthreads();
; }
; __device__ __forceinline__ void post_phase(const Params& p, int l, LAS unsigned char* lds, int tid) {
;     ...
;             for (int g = 0; g < 4; ++g) {
;                 if (isx) post_transpose<false>(px, 768 + g * 128, Lt, tid, [&](int col) { return ZT + ((size_t)((col >> 6) * 2048 + b * 256 + g * 64 + (col & 63))) * 4096 + n0; });
;                 else     post_transpose<false>(px, 768 + g * 128, Lt, tid, [&](int col) { return ZTC + ((size_t)(b * 256 + g * 64 + (col & 63))) * 512 + (col >> 6) * 256 + n0; });
;             }
.LBB0_375:
	s_andn2_b64 vcc, exec, s[0:1]
	s_cbranch_vccnz .LBB0_377
	s_barrier
	ds_read_b128 v[172:175], v107
	ds_read_b128 v[176:179], v108
	ds_read_b128 v[180:183], v109
	ds_read_b128 v[212:215], v110
	v_or_b32_e32 v4, 0xc0, v24
	v_ashrrev_i32_e32 v5, 31, v4
	v_lshlrev_b64 v[4:5], 13, v[4:5]
	v_lshl_add_u64 v[4:5], v[16:17], 0, v[4:5]
	s_waitcnt lgkmcnt(3)
	global_store_dwordx4 v[4:5], v[172:175], off
	v_or_b32_e32 v4, 0xc0, v22
	v_ashrrev_i32_e32 v5, 31, v4
	v_lshlrev_b64 v[4:5], 13, v[4:5]
	v_lshl_add_u64 v[4:5], v[16:17], 0, v[4:5]
	s_waitcnt lgkmcnt(2)
	global_store_dwordx4 v[4:5], v[176:179], off
	v_or_b32_e32 v4, 0xc0, v20
	v_ashrrev_i32_e32 v5, 31, v4
	v_lshlrev_b64 v[4:5], 13, v[4:5]
	v_lshl_add_u64 v[4:5], v[16:17], 0, v[4:5]
	s_waitcnt lgkmcnt(1)
	global_store_dwordx4 v[4:5], v[180:183], off
	v_or_b32_e32 v4, 0xc0, v18
	v_ashrrev_i32_e32 v5, 31, v4
	v_lshlrev_b64 v[4:5], 13, v[4:5]
	v_lshl_add_u64 v[4:5], v[16:17], 0, v[4:5]
	s_waitcnt lgkmcnt(0)
	global_store_dwordx4 v[4:5], v[212:215], off
	s_barrier
